# EpiRes bf16-source epilogue: 9-deep prefetch ring instead of load-wait-store per row
# speedup vs baseline: 1.0182x; 1.0182x over previous
; __device__ __forceinline__ float bf_lo(unsigned v) { return __uint_as_float(v << 16); }
; __device__ __forceinline__ float bf_hi(unsigned v) { return __uint_as_float(v & 0xffff0000u); }
;     __device__ __forceinline__ void operator()(const f32x4 (&acc)[2][2][4][2], const Unit& u, int wr, int wc, int fr, int fq) const {
;     ...
;                 const int row = row0 + ai * HALF + m * 16; const size_t ro = (size_t)row * D + col0; float ss = 0.f;
; #pragma unroll
;                 for (int bj = 0; bj < 2; ++bj) {
;                     const size_t o = ro + bj * HALF;
;                     f32x4 s0, s1;
;                     if (srcf) { s0 = *(const f32x4*)(srcf + o); s1 = *(const f32x4*)(srcf + o + 4); }
;                     else { const u32x4 w = *(const u32x4*)(srcb + o); s0 = (f32x4){bf_lo(w.x), bf_hi(w.x), bf_lo(w.y), bf_hi(w.y)}; s1 = (f32x4){bf_lo(w.z), bf_hi(w.z), bf_lo(w.w), bf_hi(w.w)}; }
;                     const f32x4 v0 = acc[ai][bj][m][0] * cs[bj][0] + s0, v1 = acc[ai][bj][m][1] * cs[bj][1] + s1;
;                     ss += v0[0] * v0[0] + v0[1] * v0[1] + v0[2] * v0[2] + v0[3] * v0[3] + v1[0] * v1[0] + v1[1] * v1[1] + v1[2] * v1[2] + v1[3] * v1[3];
;                     if (dstf) { *(f32x4*)(dstf + o) = v0; *(f32x4*)(dstf + o + 4) = v1; }
.LBB0_964:
	v_lshl_add_u32 v170, s54, 8, v197
	v_ashrrev_i32_e32 v171, 31, v170
	v_lshlrev_b64 v[144:145], 11, v[170:171]
	v_lshl_add_u64 v[172:173], v[144:145], 0, v[174:175]
	v_cndmask_b32_e64 v144, 0, 1, s[42:43]
	v_cmp_ne_u32_e64 s[12:13], 1, v144
	s_andn2_b64 vcc, exec, s[42:43]
	v_lshl_add_u64 v[180:181], v[172:173], 2, s[28:29]
	s_cbranch_vccnz .LBB0_1107
	global_load_dwordx4 v[144:147], v[180:181], off offset:16
	global_load_dwordx4 v[148:151], v[180:181], off
	v_lshl_add_u64 v[178:179], v[172:173], 1, s[84:85]
	s_waitcnt vmcnt(0)
	s_cbranch_execnz .LBB0_967
.LBB0_966:
	s_waitcnt vmcnt(8)
	v_lshlrev_b32_e32 v148, 16, v208
	v_and_b32_e32 v149, 0xffff0000, v208
	v_lshlrev_b32_e32 v150, 16, v209
	v_and_b32_e32 v151, 0xffff0000, v209
	v_lshlrev_b32_e32 v144, 16, v210
	v_and_b32_e32 v145, 0xffff0000, v210
	v_lshlrev_b32_e32 v146, 16, v211
	v_and_b32_e32 v147, 0xffff0000, v211
	v_add_u32_e32 v179, 0x80000, v178
	global_load_dwordx4 v[208:211], v179, s[84:85] offset:256
.LBB0_967:
	v_pk_fma_f32 v[136:137], v[136:137], v[60:61], v[144:145]
	v_cndmask_b32_e64 v144, 0, 1, s[44:45]
	v_pk_fma_f32 v[142:143], v[142:143], v[70:71], v[150:151]
	v_pk_fma_f32 v[140:141], v[140:141], v[68:69], v[148:149]
	v_pk_fma_f32 v[138:139], v[138:139], v[62:63], v[146:147]
	v_cmp_ne_u32_e64 s[14:15], 1, v144
	s_andn2_b64 vcc, exec, s[44:45]
	v_lshl_add_u64 v[182:183], v[172:173], 2, s[20:21]
	s_cbranch_vccnz .LBB0_969
	global_store_dwordx4 v[182:183], v[140:143], off
	global_store_dwordx4 v[182:183], v[136:139], off offset:16

; __device__ __forceinline__ float bf_lo(unsigned v) { return __uint_as_float(v << 16); }
; __device__ __forceinline__ float bf_hi(unsigned v) { return __uint_as_float(v & 0xffff0000u); }
;     __device__ __forceinline__ void operator()(const f32x4 (&acc)[2][2][4][2], const Unit& u, int wr, int wc, int fr, int fq) const {
;     ...
;                 const int row = row0 + ai * HALF + m * 16; const size_t ro = (size_t)row * D + col0; float ss = 0.f;
; #pragma unroll
;                 for (int bj = 0; bj < 2; ++bj) {
;                     const size_t o = ro + bj * HALF;
;                     f32x4 s0, s1;
;                     if (srcf) { s0 = *(const f32x4*)(srcf + o); s1 = *(const f32x4*)(srcf + o + 4); }
;                     else { const u32x4 w = *(const u32x4*)(srcb + o); s0 = (f32x4){bf_lo(w.x), bf_hi(w.x), bf_lo(w.y), bf_hi(w.y)}; s1 = (f32x4){bf_lo(w.z), bf_hi(w.z), bf_lo(w.w), bf_hi(w.w)}; }
;                     const f32x4 v0 = acc[ai][bj][m][0] * cs[bj][0] + s0, v1 = acc[ai][bj][m][1] * cs[bj][1] + s1;
;                     ss += v0[0] * v0[0] + v0[1] * v0[1] + v0[2] * v0[2] + v0[3] * v0[3] + v1[0] * v1[0] + v1[1] * v1[1] + v1[2] * v1[2] + v1[3] * v1[3];
;                     if (dstf) { *(f32x4*)(dstf + o) = v0; *(f32x4*)(dstf + o + 4) = v1; }
.LBB0_971:
	s_and_b64 vcc, exec, s[12:13]
	s_cbranch_vccnz .LBB0_1108
	global_load_dwordx4 v[144:147], v[180:181], off offset:528
	global_load_dwordx4 v[148:151], v[180:181], off offset:512
	s_waitcnt vmcnt(0)
	s_cbranch_execnz .LBB0_974
.LBB0_973:
	s_waitcnt vmcnt(9)
	v_lshlrev_b32_e32 v148, 16, v212
	v_and_b32_e32 v149, 0xffff0000, v212
	v_lshlrev_b32_e32 v150, 16, v213
	v_and_b32_e32 v151, 0xffff0000, v213
	v_lshlrev_b32_e32 v144, 16, v214
	v_and_b32_e32 v145, 0xffff0000, v214
	v_lshlrev_b32_e32 v146, 16, v215
	v_and_b32_e32 v147, 0xffff0000, v215
	v_add_u32_e32 v179, 0x90000, v178
	global_load_dwordx4 v[212:215], v179, s[84:85]
.LBB0_974:
	v_pk_fma_f32 v[134:135], v[134:135], v[54:55], v[150:151]
	v_pk_fma_f32 v[132:133], v[132:133], v[52:53], v[148:149]
	v_pk_fma_f32 v[130:131], v[130:131], v[50:51], v[146:147]
	s_and_b64 vcc, exec, s[14:15]
	v_pk_fma_f32 v[128:129], v[128:129], v[48:49], v[144:145]
	s_cbranch_vccnz .LBB0_976
	global_store_dwordx4 v[182:183], v[132:135], off offset:512
	global_store_dwordx4 v[182:183], v[128:131], off offset:528

; __device__ __forceinline__ float bf_lo(unsigned v) { return __uint_as_float(v << 16); }
; __device__ __forceinline__ float bf_hi(unsigned v) { return __uint_as_float(v & 0xffff0000u); }
;     __device__ __forceinline__ void operator()(const f32x4 (&acc)[2][2][4][2], const Unit& u, int wr, int wc, int fr, int fq) const {
;     ...
;                 const int row = row0 + ai * HALF + m * 16; const size_t ro = (size_t)row * D + col0; float ss = 0.f;
; #pragma unroll
;                 for (int bj = 0; bj < 2; ++bj) {
;                     const size_t o = ro + bj * HALF;
;                     f32x4 s0, s1;
;                     if (srcf) { s0 = *(const f32x4*)(srcf + o); s1 = *(const f32x4*)(srcf + o + 4); }
;                     else { const u32x4 w = *(const u32x4*)(srcb + o); s0 = (f32x4){bf_lo(w.x), bf_hi(w.x), bf_lo(w.y), bf_hi(w.y)}; s1 = (f32x4){bf_lo(w.z), bf_hi(w.z), bf_lo(w.w), bf_hi(w.w)}; }
;                     const f32x4 v0 = acc[ai][bj][m][0] * cs[bj][0] + s0, v1 = acc[ai][bj][m][1] * cs[bj][1] + s1;
;                     ss += v0[0] * v0[0] + v0[1] * v0[1] + v0[2] * v0[2] + v0[3] * v0[3] + v1[0] * v1[0] + v1[1] * v1[1] + v1[2] * v1[2] + v1[3] * v1[3];
;                     if (dstf) { *(f32x4*)(dstf + o) = v0; *(f32x4*)(dstf + o + 4) = v1; }
.LBB0_982:
	v_or_b32_e32 v128, 16, v170
	s_waitcnt lgkmcnt(0)
	v_ashrrev_i32_e32 v129, 31, v128
	v_lshlrev_b64 v[128:129], 11, v[128:129]
	v_lshl_add_u64 v[136:137], v[128:129], 0, v[174:175]
	s_and_b64 vcc, exec, s[12:13]
	v_lshl_add_u64 v[142:143], v[136:137], 2, s[28:29]
	s_cbranch_vccnz .LBB0_1109
	global_load_dwordx4 v[128:131], v[142:143], off offset:16
	global_load_dwordx4 v[132:135], v[142:143], off
	v_lshl_add_u64 v[138:139], v[136:137], 1, s[84:85]
	s_waitcnt vmcnt(0)
	s_cbranch_execnz .LBB0_985
.LBB0_984:
	s_waitcnt vmcnt(10)
	v_lshlrev_b32_e32 v132, 16, v216
	v_and_b32_e32 v133, 0xffff0000, v216
	v_lshlrev_b32_e32 v134, 16, v217
	v_and_b32_e32 v135, 0xffff0000, v217
	v_lshlrev_b32_e32 v128, 16, v218
	v_and_b32_e32 v129, 0xffff0000, v218
	v_lshlrev_b32_e32 v130, 16, v219
	v_and_b32_e32 v131, 0xffff0000, v219
	v_add_u32_e32 v179, 0x90000, v178
	global_load_dwordx4 v[216:219], v179, s[84:85] offset:256
.LBB0_985:
	v_pk_fma_f32 v[126:127], v[126:127], v[70:71], v[134:135]
	v_pk_fma_f32 v[124:125], v[124:125], v[68:69], v[132:133]
	v_pk_fma_f32 v[122:123], v[122:123], v[62:63], v[130:131]
	v_pk_fma_f32 v[120:121], v[120:121], v[60:61], v[128:129]
	s_and_b64 vcc, exec, s[14:15]
	v_lshl_add_u64 v[140:141], v[136:137], 2, s[20:21]
	s_cbranch_vccnz .LBB0_987
	global_store_dwordx4 v[140:141], v[124:127], off
	global_store_dwordx4 v[140:141], v[120:123], off offset:16

; __device__ __forceinline__ float bf_lo(unsigned v) { return __uint_as_float(v << 16); }
; __device__ __forceinline__ float bf_hi(unsigned v) { return __uint_as_float(v & 0xffff0000u); }
;     __device__ __forceinline__ void operator()(const f32x4 (&acc)[2][2][4][2], const Unit& u, int wr, int wc, int fr, int fq) const {
;     ...
;                 const int row = row0 + ai * HALF + m * 16; const size_t ro = (size_t)row * D + col0; float ss = 0.f;
; #pragma unroll
;                 for (int bj = 0; bj < 2; ++bj) {
;                     const size_t o = ro + bj * HALF;
;                     f32x4 s0, s1;
;                     if (srcf) { s0 = *(const f32x4*)(srcf + o); s1 = *(const f32x4*)(srcf + o + 4); }
;                     else { const u32x4 w = *(const u32x4*)(srcb + o); s0 = (f32x4){bf_lo(w.x), bf_hi(w.x), bf_lo(w.y), bf_hi(w.y)}; s1 = (f32x4){bf_lo(w.z), bf_hi(w.z), bf_lo(w.w), bf_hi(w.w)}; }
;                     const f32x4 v0 = acc[ai][bj][m][0] * cs[bj][0] + s0, v1 = acc[ai][bj][m][1] * cs[bj][1] + s1;
;                     ss += v0[0] * v0[0] + v0[1] * v0[1] + v0[2] * v0[2] + v0[3] * v0[3] + v1[0] * v1[0] + v1[1] * v1[1] + v1[2] * v1[2] + v1[3] * v1[3];
;                     if (dstf) { *(f32x4*)(dstf + o) = v0; *(f32x4*)(dstf + o + 4) = v1; }
.LBB0_989:
	s_and_b64 vcc, exec, s[12:13]
	s_cbranch_vccnz .LBB0_1110
	global_load_dwordx4 v[128:131], v[142:143], off offset:528
	global_load_dwordx4 v[132:135], v[142:143], off offset:512
	s_waitcnt vmcnt(0)
	s_cbranch_execnz .LBB0_992
.LBB0_991:
	s_waitcnt vmcnt(11)
	v_lshlrev_b32_e32 v132, 16, v220
	v_and_b32_e32 v133, 0xffff0000, v220
	v_lshlrev_b32_e32 v134, 16, v221
	v_and_b32_e32 v135, 0xffff0000, v221
	v_lshlrev_b32_e32 v128, 16, v222
	v_and_b32_e32 v129, 0xffff0000, v222
	v_lshlrev_b32_e32 v130, 16, v223
	v_and_b32_e32 v131, 0xffff0000, v223
	v_add_u32_e32 v179, 0xa0000, v178
	global_load_dwordx4 v[220:223], v179, s[84:85]
.LBB0_992:
	v_pk_fma_f32 v[118:119], v[118:119], v[54:55], v[134:135]
	v_pk_fma_f32 v[116:117], v[116:117], v[52:53], v[132:133]
	v_pk_fma_f32 v[114:115], v[114:115], v[50:51], v[130:131]
	s_and_b64 vcc, exec, s[14:15]
	v_pk_fma_f32 v[112:113], v[112:113], v[48:49], v[128:129]
	s_cbranch_vccnz .LBB0_994
	global_store_dwordx4 v[140:141], v[116:119], off offset:512
	global_store_dwordx4 v[140:141], v[112:115], off offset:528

; __device__ __forceinline__ float bf_lo(unsigned v) { return __uint_as_float(v << 16); }
; __device__ __forceinline__ float bf_hi(unsigned v) { return __uint_as_float(v & 0xffff0000u); }
;     __device__ __forceinline__ void operator()(const f32x4 (&acc)[2][2][4][2], const Unit& u, int wr, int wc, int fr, int fq) const {
;     ...
;                 const int row = row0 + ai * HALF + m * 16; const size_t ro = (size_t)row * D + col0; float ss = 0.f;
; #pragma unroll
;                 for (int bj = 0; bj < 2; ++bj) {
;                     const size_t o = ro + bj * HALF;
;                     f32x4 s0, s1;
;                     if (srcf) { s0 = *(const f32x4*)(srcf + o); s1 = *(const f32x4*)(srcf + o + 4); }
;                     else { const u32x4 w = *(const u32x4*)(srcb + o); s0 = (f32x4){bf_lo(w.x), bf_hi(w.x), bf_lo(w.y), bf_hi(w.y)}; s1 = (f32x4){bf_lo(w.z), bf_hi(w.z), bf_lo(w.w), bf_hi(w.w)}; }
;                     const f32x4 v0 = acc[ai][bj][m][0] * cs[bj][0] + s0, v1 = acc[ai][bj][m][1] * cs[bj][1] + s1;
;                     ss += v0[0] * v0[0] + v0[1] * v0[1] + v0[2] * v0[2] + v0[3] * v0[3] + v1[0] * v1[0] + v1[1] * v1[1] + v1[2] * v1[2] + v1[3] * v1[3];
;                     if (dstf) { *(f32x4*)(dstf + o) = v0; *(f32x4*)(dstf + o + 4) = v1; }
.LBB0_1000:
	v_or_b32_e32 v112, 32, v170
	s_waitcnt lgkmcnt(0)
	v_ashrrev_i32_e32 v113, 31, v112
	v_lshlrev_b64 v[112:113], 11, v[112:113]
	v_lshl_add_u64 v[120:121], v[112:113], 0, v[174:175]
	s_and_b64 vcc, exec, s[12:13]
	v_lshl_add_u64 v[126:127], v[120:121], 2, s[28:29]
	s_cbranch_vccnz .LBB0_1111
	global_load_dwordx4 v[112:115], v[126:127], off offset:16
	global_load_dwordx4 v[116:119], v[126:127], off
	v_lshl_add_u64 v[122:123], v[120:121], 1, s[84:85]
	s_waitcnt vmcnt(0)
	s_cbranch_execnz .LBB0_1003
.LBB0_1002:
	s_waitcnt vmcnt(12)
	v_lshlrev_b32_e32 v116, 16, v224
	v_and_b32_e32 v117, 0xffff0000, v224
	v_lshlrev_b32_e32 v118, 16, v225
	v_and_b32_e32 v119, 0xffff0000, v225
	v_lshlrev_b32_e32 v112, 16, v226
	v_and_b32_e32 v113, 0xffff0000, v226
	v_lshlrev_b32_e32 v114, 16, v227
	v_and_b32_e32 v115, 0xffff0000, v227
	v_add_u32_e32 v179, 0xa0000, v178
	global_load_dwordx4 v[224:227], v179, s[84:85] offset:256
.LBB0_1003:
	v_pk_fma_f32 v[110:111], v[110:111], v[70:71], v[118:119]
	v_pk_fma_f32 v[108:109], v[108:109], v[68:69], v[116:117]
	v_pk_fma_f32 v[106:107], v[106:107], v[62:63], v[114:115]
	v_pk_fma_f32 v[104:105], v[104:105], v[60:61], v[112:113]
	s_and_b64 vcc, exec, s[14:15]
	v_lshl_add_u64 v[124:125], v[120:121], 2, s[20:21]
	s_cbranch_vccnz .LBB0_1005
	global_store_dwordx4 v[124:125], v[108:111], off
	global_store_dwordx4 v[124:125], v[104:107], off offset:16

; __device__ __forceinline__ float bf_lo(unsigned v) { return __uint_as_float(v << 16); }
; __device__ __forceinline__ float bf_hi(unsigned v) { return __uint_as_float(v & 0xffff0000u); }
;     __device__ __forceinline__ void operator()(const f32x4 (&acc)[2][2][4][2], const Unit& u, int wr, int wc, int fr, int fq) const {
;     ...
;                 const int row = row0 + ai * HALF + m * 16; const size_t ro = (size_t)row * D + col0; float ss = 0.f;
; #pragma unroll
;                 for (int bj = 0; bj < 2; ++bj) {
;                     const size_t o = ro + bj * HALF;
;                     f32x4 s0, s1;
;                     if (srcf) { s0 = *(const f32x4*)(srcf + o); s1 = *(const f32x4*)(srcf + o + 4); }
;                     else { const u32x4 w = *(const u32x4*)(srcb + o); s0 = (f32x4){bf_lo(w.x), bf_hi(w.x), bf_lo(w.y), bf_hi(w.y)}; s1 = (f32x4){bf_lo(w.z), bf_hi(w.z), bf_lo(w.w), bf_hi(w.w)}; }
;                     const f32x4 v0 = acc[ai][bj][m][0] * cs[bj][0] + s0, v1 = acc[ai][bj][m][1] * cs[bj][1] + s1;
;                     ss += v0[0] * v0[0] + v0[1] * v0[1] + v0[2] * v0[2] + v0[3] * v0[3] + v1[0] * v1[0] + v1[1] * v1[1] + v1[2] * v1[2] + v1[3] * v1[3];
;                     if (dstf) { *(f32x4*)(dstf + o) = v0; *(f32x4*)(dstf + o + 4) = v1; }
.LBB0_1007:
	s_and_b64 vcc, exec, s[12:13]
	s_cbranch_vccnz .LBB0_1112
	global_load_dwordx4 v[112:115], v[126:127], off offset:528
	global_load_dwordx4 v[116:119], v[126:127], off offset:512
	s_waitcnt vmcnt(0)
	s_cbranch_execnz .LBB0_1010
.LBB0_1009:
	s_waitcnt vmcnt(13)
	v_lshlrev_b32_e32 v116, 16, v228
	v_and_b32_e32 v117, 0xffff0000, v228
	v_lshlrev_b32_e32 v118, 16, v229
	v_and_b32_e32 v119, 0xffff0000, v229
	v_lshlrev_b32_e32 v112, 16, v230
	v_and_b32_e32 v113, 0xffff0000, v230
	v_lshlrev_b32_e32 v114, 16, v231
	v_and_b32_e32 v115, 0xffff0000, v231
	v_add_u32_e32 v179, 0xb0000, v178
	global_load_dwordx4 v[228:231], v179, s[84:85]
.LBB0_1010:
	v_pk_fma_f32 v[102:103], v[102:103], v[54:55], v[118:119]
	v_pk_fma_f32 v[100:101], v[100:101], v[52:53], v[116:117]
	v_pk_fma_f32 v[98:99], v[98:99], v[50:51], v[114:115]
	s_and_b64 vcc, exec, s[14:15]
	v_pk_fma_f32 v[96:97], v[96:97], v[48:49], v[112:113]
	s_cbranch_vccnz .LBB0_1012
	global_store_dwordx4 v[124:125], v[100:103], off offset:512
	global_store_dwordx4 v[124:125], v[96:99], off offset:528

; __device__ __forceinline__ float bf_lo(unsigned v) { return __uint_as_float(v << 16); }
; __device__ __forceinline__ float bf_hi(unsigned v) { return __uint_as_float(v & 0xffff0000u); }
;     __device__ __forceinline__ void operator()(const f32x4 (&acc)[2][2][4][2], const Unit& u, int wr, int wc, int fr, int fq) const {
;     ...
;                 const int row = row0 + ai * HALF + m * 16; const size_t ro = (size_t)row * D + col0; float ss = 0.f;
; #pragma unroll
;                 for (int bj = 0; bj < 2; ++bj) {
;                     const size_t o = ro + bj * HALF;
;                     f32x4 s0, s1;
;                     if (srcf) { s0 = *(const f32x4*)(srcf + o); s1 = *(const f32x4*)(srcf + o + 4); }
;                     else { const u32x4 w = *(const u32x4*)(srcb + o); s0 = (f32x4){bf_lo(w.x), bf_hi(w.x), bf_lo(w.y), bf_hi(w.y)}; s1 = (f32x4){bf_lo(w.z), bf_hi(w.z), bf_lo(w.w), bf_hi(w.w)}; }
;                     const f32x4 v0 = acc[ai][bj][m][0] * cs[bj][0] + s0, v1 = acc[ai][bj][m][1] * cs[bj][1] + s1;
;                     ss += v0[0] * v0[0] + v0[1] * v0[1] + v0[2] * v0[2] + v0[3] * v0[3] + v1[0] * v1[0] + v1[1] * v1[1] + v1[2] * v1[2] + v1[3] * v1[3];
;                     if (dstf) { *(f32x4*)(dstf + o) = v0; *(f32x4*)(dstf + o + 4) = v1; }
.LBB0_1018:
	v_or_b32_e32 v96, 48, v170
	s_waitcnt lgkmcnt(0)
	v_ashrrev_i32_e32 v97, 31, v96
	v_lshlrev_b64 v[96:97], 11, v[96:97]
	v_lshl_add_u64 v[104:105], v[96:97], 0, v[174:175]
	s_and_b64 vcc, exec, s[12:13]
	v_lshl_add_u64 v[110:111], v[104:105], 2, s[28:29]
	s_cbranch_vccnz .LBB0_1113
	global_load_dwordx4 v[96:99], v[110:111], off offset:16
	global_load_dwordx4 v[100:103], v[110:111], off
	v_lshl_add_u64 v[106:107], v[104:105], 1, s[84:85]
	s_waitcnt vmcnt(0)
	s_cbranch_execnz .LBB0_1021
.LBB0_1020:
	s_waitcnt vmcnt(14)
	v_lshlrev_b32_e32 v100, 16, v232
	v_and_b32_e32 v101, 0xffff0000, v232
	v_lshlrev_b32_e32 v102, 16, v233
	v_and_b32_e32 v103, 0xffff0000, v233
	v_lshlrev_b32_e32 v96, 16, v234
	v_and_b32_e32 v97, 0xffff0000, v234
	v_lshlrev_b32_e32 v98, 16, v235
	v_and_b32_e32 v99, 0xffff0000, v235
	v_add_u32_e32 v179, 0xb0000, v178
	global_load_dwordx4 v[232:235], v179, s[84:85] offset:256
.LBB0_1021:
	v_pk_fma_f32 v[94:95], v[94:95], v[70:71], v[102:103]
	v_pk_fma_f32 v[92:93], v[92:93], v[68:69], v[100:101]
	v_pk_fma_f32 v[90:91], v[90:91], v[62:63], v[98:99]
	v_pk_fma_f32 v[88:89], v[88:89], v[60:61], v[96:97]
	s_and_b64 vcc, exec, s[14:15]
	v_lshl_add_u64 v[108:109], v[104:105], 2, s[20:21]
	s_cbranch_vccnz .LBB0_1023
	global_store_dwordx4 v[108:109], v[92:95], off
	global_store_dwordx4 v[108:109], v[88:91], off offset:16

; __device__ __forceinline__ float bf_lo(unsigned v) { return __uint_as_float(v << 16); }
; __device__ __forceinline__ float bf_hi(unsigned v) { return __uint_as_float(v & 0xffff0000u); }
;     __device__ __forceinline__ void operator()(const f32x4 (&acc)[2][2][4][2], const Unit& u, int wr, int wc, int fr, int fq) const {
;     ...
;                 const int row = row0 + ai * HALF + m * 16; const size_t ro = (size_t)row * D + col0; float ss = 0.f;
; #pragma unroll
;                 for (int bj = 0; bj < 2; ++bj) {
;                     const size_t o = ro + bj * HALF;
;                     f32x4 s0, s1;
;                     if (srcf) { s0 = *(const f32x4*)(srcf + o); s1 = *(const f32x4*)(srcf + o + 4); }
;                     else { const u32x4 w = *(const u32x4*)(srcb + o); s0 = (f32x4){bf_lo(w.x), bf_hi(w.x), bf_lo(w.y), bf_hi(w.y)}; s1 = (f32x4){bf_lo(w.z), bf_hi(w.z), bf_lo(w.w), bf_hi(w.w)}; }
;                     const f32x4 v0 = acc[ai][bj][m][0] * cs[bj][0] + s0, v1 = acc[ai][bj][m][1] * cs[bj][1] + s1;
;                     ss += v0[0] * v0[0] + v0[1] * v0[1] + v0[2] * v0[2] + v0[3] * v0[3] + v1[0] * v1[0] + v1[1] * v1[1] + v1[2] * v1[2] + v1[3] * v1[3];
;                     if (dstf) { *(f32x4*)(dstf + o) = v0; *(f32x4*)(dstf + o + 4) = v1; }
.LBB0_1025:
	s_and_b64 vcc, exec, s[12:13]
	s_cbranch_vccnz .LBB0_1114
	global_load_dwordx4 v[96:99], v[110:111], off offset:528
	global_load_dwordx4 v[100:103], v[110:111], off offset:512
	s_waitcnt vmcnt(0)
	s_cbranch_execnz .LBB0_1028
.LBB0_1027:
	s_waitcnt vmcnt(15)
	v_lshlrev_b32_e32 v100, 16, v246
	v_and_b32_e32 v101, 0xffff0000, v246
	v_lshlrev_b32_e32 v102, 16, v247
	v_and_b32_e32 v103, 0xffff0000, v247
	v_lshlrev_b32_e32 v96, 16, v248
	v_and_b32_e32 v97, 0xffff0000, v248
	v_lshlrev_b32_e32 v98, 16, v249
	v_and_b32_e32 v99, 0xffff0000, v249
.LBB0_1028:
	v_pk_fma_f32 v[86:87], v[86:87], v[54:55], v[102:103]
	v_pk_fma_f32 v[84:85], v[84:85], v[52:53], v[100:101]
	v_pk_fma_f32 v[82:83], v[82:83], v[50:51], v[98:99]
	s_and_b64 vcc, exec, s[14:15]
	v_pk_fma_f32 v[80:81], v[80:81], v[48:49], v[96:97]
	s_cbranch_vccnz .LBB0_1030
	global_store_dwordx4 v[108:109], v[84:87], off offset:512
	global_store_dwordx4 v[108:109], v[80:83], off offset:528

; __device__ __forceinline__ float bf_lo(unsigned v) { return __uint_as_float(v << 16); }
; __device__ __forceinline__ float bf_hi(unsigned v) { return __uint_as_float(v & 0xffff0000u); }
;     __device__ __forceinline__ void operator()(const f32x4 (&acc)[2][2][4][2], const Unit& u, int wr, int wc, int fr, int fq) const {
;     ...
;                 const int row = row0 + ai * HALF + m * 16; const size_t ro = (size_t)row * D + col0; float ss = 0.f;
; #pragma unroll
;                 for (int bj = 0; bj < 2; ++bj) {
;                     const size_t o = ro + bj * HALF;
;                     f32x4 s0, s1;
;                     if (srcf) { s0 = *(const f32x4*)(srcf + o); s1 = *(const f32x4*)(srcf + o + 4); }
;                     else { const u32x4 w = *(const u32x4*)(srcb + o); s0 = (f32x4){bf_lo(w.x), bf_hi(w.x), bf_lo(w.y), bf_hi(w.y)}; s1 = (f32x4){bf_lo(w.z), bf_hi(w.z), bf_lo(w.w), bf_hi(w.w)}; }
;                     const f32x4 v0 = acc[ai][bj][m][0] * cs[bj][0] + s0, v1 = acc[ai][bj][m][1] * cs[bj][1] + s1;
;                     ss += v0[0] * v0[0] + v0[1] * v0[1] + v0[2] * v0[2] + v0[3] * v0[3] + v1[0] * v1[0] + v1[1] * v1[1] + v1[2] * v1[2] + v1[3] * v1[3];
;                     if (dstf) { *(f32x4*)(dstf + o) = v0; *(f32x4*)(dstf + o + 4) = v1; }
.LBB0_1036:
	s_mov_b64 s[54:55], 0x40000
	v_lshl_add_u64 v[88:89], v[172:173], 0, s[54:55]
	s_and_b64 vcc, exec, s[12:13]
	v_lshl_add_u64 v[94:95], v[88:89], 2, s[28:29]
	s_cbranch_vccnz .LBB0_1115
	s_waitcnt lgkmcnt(0)
	global_load_dwordx4 v[80:83], v[94:95], off offset:16
	global_load_dwordx4 v[84:87], v[94:95], off
	v_lshl_add_u64 v[90:91], v[88:89], 1, s[84:85]
	s_waitcnt vmcnt(0)
	s_cbranch_execnz .LBB0_1039
.LBB0_1038:
	s_waitcnt lgkmcnt(0)
	s_waitcnt vmcnt(15)
	v_lshlrev_b32_e32 v84, 16, v250
	v_and_b32_e32 v85, 0xffff0000, v250
	v_lshlrev_b32_e32 v86, 16, v251
	v_and_b32_e32 v87, 0xffff0000, v251
	v_lshlrev_b32_e32 v80, 16, v252
	v_and_b32_e32 v81, 0xffff0000, v252
	v_lshlrev_b32_e32 v82, 16, v253
	v_and_b32_e32 v83, 0xffff0000, v253
.LBB0_1039:
	v_pk_fma_f32 v[78:79], v[78:79], v[70:71], v[86:87]
	v_pk_fma_f32 v[76:77], v[76:77], v[68:69], v[84:85]
	v_pk_fma_f32 v[74:75], v[74:75], v[62:63], v[82:83]
	s_waitcnt lgkmcnt(0)
	v_pk_fma_f32 v[72:73], v[72:73], v[60:61], v[80:81]
	s_and_b64 vcc, exec, s[14:15]
	v_lshl_add_u64 v[92:93], v[88:89], 2, s[20:21]
	s_cbranch_vccnz .LBB0_1041
	global_store_dwordx4 v[92:93], v[76:79], off
	global_store_dwordx4 v[92:93], v[72:75], off offset:16

; __device__ __forceinline__ float bf_lo(unsigned v) { return __uint_as_float(v << 16); }
; __device__ __forceinline__ float bf_hi(unsigned v) { return __uint_as_float(v & 0xffff0000u); }
;     __device__ __forceinline__ void operator()(const f32x4 (&acc)[2][2][4][2], const Unit& u, int wr, int wc, int fr, int fq) const {
;     ...
;                 const int row = row0 + ai * HALF + m * 16; const size_t ro = (size_t)row * D + col0; float ss = 0.f;
; #pragma unroll
;                 for (int bj = 0; bj < 2; ++bj) {
;                     const size_t o = ro + bj * HALF;
;                     f32x4 s0, s1;
;                     if (srcf) { s0 = *(const f32x4*)(srcf + o); s1 = *(const f32x4*)(srcf + o + 4); }
;                     else { const u32x4 w = *(const u32x4*)(srcb + o); s0 = (f32x4){bf_lo(w.x), bf_hi(w.x), bf_lo(w.y), bf_hi(w.y)}; s1 = (f32x4){bf_lo(w.z), bf_hi(w.z), bf_lo(w.w), bf_hi(w.w)}; }
;                     const f32x4 v0 = acc[ai][bj][m][0] * cs[bj][0] + s0, v1 = acc[ai][bj][m][1] * cs[bj][1] + s1;
;                     ss += v0[0] * v0[0] + v0[1] * v0[1] + v0[2] * v0[2] + v0[3] * v0[3] + v1[0] * v1[0] + v1[1] * v1[1] + v1[2] * v1[2] + v1[3] * v1[3];
;                     if (dstf) { *(f32x4*)(dstf + o) = v0; *(f32x4*)(dstf + o + 4) = v1; }
.LBB0_1043:
	s_and_b64 vcc, exec, s[12:13]
	s_cbranch_vccnz .LBB0_1116
	global_load_dwordx4 v[80:83], v[94:95], off offset:528
	global_load_dwordx4 v[84:87], v[94:95], off offset:512
	s_waitcnt vmcnt(0)
	s_cbranch_execnz .LBB0_1046
.LBB0_1045:
	s_waitcnt vmcnt(15)
	v_lshlrev_b32_e32 v84, 16, v208
	v_and_b32_e32 v85, 0xffff0000, v208
	v_lshlrev_b32_e32 v86, 16, v209
	v_and_b32_e32 v87, 0xffff0000, v209
	v_lshlrev_b32_e32 v80, 16, v210
	v_and_b32_e32 v81, 0xffff0000, v210
	v_lshlrev_b32_e32 v82, 16, v211
	v_and_b32_e32 v83, 0xffff0000, v211
.LBB0_1046:
	v_pk_fma_f32 v[66:67], v[66:67], v[54:55], v[86:87]
	v_pk_fma_f32 v[64:65], v[64:65], v[52:53], v[84:85]
	v_pk_fma_f32 v[58:59], v[58:59], v[50:51], v[82:83]
	s_and_b64 vcc, exec, s[14:15]
	v_pk_fma_f32 v[56:57], v[56:57], v[48:49], v[80:81]
	s_cbranch_vccnz .LBB0_1048
	global_store_dwordx4 v[92:93], v[64:67], off offset:512
	global_store_dwordx4 v[92:93], v[56:59], off offset:528

; __device__ __forceinline__ float bf_lo(unsigned v) { return __uint_as_float(v << 16); }
; __device__ __forceinline__ float bf_hi(unsigned v) { return __uint_as_float(v & 0xffff0000u); }
;     __device__ __forceinline__ void operator()(const f32x4 (&acc)[2][2][4][2], const Unit& u, int wr, int wc, int fr, int fq) const {
;     ...
;                 const int row = row0 + ai * HALF + m * 16; const size_t ro = (size_t)row * D + col0; float ss = 0.f;
; #pragma unroll
;                 for (int bj = 0; bj < 2; ++bj) {
;                     const size_t o = ro + bj * HALF;
;                     f32x4 s0, s1;
;                     if (srcf) { s0 = *(const f32x4*)(srcf + o); s1 = *(const f32x4*)(srcf + o + 4); }
;                     else { const u32x4 w = *(const u32x4*)(srcb + o); s0 = (f32x4){bf_lo(w.x), bf_hi(w.x), bf_lo(w.y), bf_hi(w.y)}; s1 = (f32x4){bf_lo(w.z), bf_hi(w.z), bf_lo(w.w), bf_hi(w.w)}; }
;                     const f32x4 v0 = acc[ai][bj][m][0] * cs[bj][0] + s0, v1 = acc[ai][bj][m][1] * cs[bj][1] + s1;
;                     ss += v0[0] * v0[0] + v0[1] * v0[1] + v0[2] * v0[2] + v0[3] * v0[3] + v1[0] * v1[0] + v1[1] * v1[1] + v1[2] * v1[2] + v1[3] * v1[3];
;                     if (dstf) { *(f32x4*)(dstf + o) = v0; *(f32x4*)(dstf + o + 4) = v1; }
.LBB0_1054:
	s_mov_b64 s[54:55], 0x48000
	v_lshl_add_u64 v[72:73], v[172:173], 0, s[54:55]
	s_and_b64 vcc, exec, s[12:13]
	v_lshl_add_u64 v[78:79], v[72:73], 2, s[28:29]
	s_cbranch_vccnz .LBB0_1117
	s_waitcnt lgkmcnt(0)
	global_load_dwordx4 v[56:59], v[78:79], off offset:16
	global_load_dwordx4 v[64:67], v[78:79], off
	v_lshl_add_u64 v[74:75], v[72:73], 1, s[84:85]
	s_waitcnt vmcnt(0)
	s_cbranch_execnz .LBB0_1057
.LBB0_1056:
	s_waitcnt lgkmcnt(0)
	s_waitcnt vmcnt(14)
	v_lshlrev_b32_e32 v64, 16, v212
	v_and_b32_e32 v65, 0xffff0000, v212
	v_lshlrev_b32_e32 v66, 16, v213
	v_and_b32_e32 v67, 0xffff0000, v213
	v_lshlrev_b32_e32 v56, 16, v214
	v_and_b32_e32 v57, 0xffff0000, v214
	v_lshlrev_b32_e32 v58, 16, v215
	v_and_b32_e32 v59, 0xffff0000, v215
.LBB0_1057:
	v_pk_fma_f32 v[46:47], v[46:47], v[70:71], v[66:67]
	v_pk_fma_f32 v[44:45], v[44:45], v[68:69], v[64:65]
	v_pk_fma_f32 v[42:43], v[42:43], v[62:63], v[58:59]
	s_waitcnt lgkmcnt(0)
	v_pk_fma_f32 v[40:41], v[40:41], v[60:61], v[56:57]
	s_and_b64 vcc, exec, s[14:15]
	v_lshl_add_u64 v[76:77], v[72:73], 2, s[20:21]
	s_cbranch_vccnz .LBB0_1059
	global_store_dwordx4 v[76:77], v[44:47], off
	global_store_dwordx4 v[76:77], v[40:43], off offset:16

; __device__ __forceinline__ float bf_lo(unsigned v) { return __uint_as_float(v << 16); }
; __device__ __forceinline__ float bf_hi(unsigned v) { return __uint_as_float(v & 0xffff0000u); }
;     __device__ __forceinline__ void operator()(const f32x4 (&acc)[2][2][4][2], const Unit& u, int wr, int wc, int fr, int fq) const {
;     ...
;                 const int row = row0 + ai * HALF + m * 16; const size_t ro = (size_t)row * D + col0; float ss = 0.f;
; #pragma unroll
;                 for (int bj = 0; bj < 2; ++bj) {
;                     const size_t o = ro + bj * HALF;
;                     f32x4 s0, s1;
;                     if (srcf) { s0 = *(const f32x4*)(srcf + o); s1 = *(const f32x4*)(srcf + o + 4); }
;                     else { const u32x4 w = *(const u32x4*)(srcb + o); s0 = (f32x4){bf_lo(w.x), bf_hi(w.x), bf_lo(w.y), bf_hi(w.y)}; s1 = (f32x4){bf_lo(w.z), bf_hi(w.z), bf_lo(w.w), bf_hi(w.w)}; }
;                     const f32x4 v0 = acc[ai][bj][m][0] * cs[bj][0] + s0, v1 = acc[ai][bj][m][1] * cs[bj][1] + s1;
;                     ss += v0[0] * v0[0] + v0[1] * v0[1] + v0[2] * v0[2] + v0[3] * v0[3] + v1[0] * v1[0] + v1[1] * v1[1] + v1[2] * v1[2] + v1[3] * v1[3];
;                     if (dstf) { *(f32x4*)(dstf + o) = v0; *(f32x4*)(dstf + o + 4) = v1; }
.LBB0_1061:
	s_and_b64 vcc, exec, s[12:13]
	s_cbranch_vccnz .LBB0_1118
	global_load_dwordx4 v[56:59], v[78:79], off offset:528
	global_load_dwordx4 v[64:67], v[78:79], off offset:512
	s_waitcnt vmcnt(0)
	s_cbranch_execnz .LBB0_1064
.LBB0_1063:
	s_waitcnt vmcnt(13)
	v_lshlrev_b32_e32 v64, 16, v216
	v_and_b32_e32 v65, 0xffff0000, v216
	v_lshlrev_b32_e32 v66, 16, v217
	v_and_b32_e32 v67, 0xffff0000, v217
	v_lshlrev_b32_e32 v56, 16, v218
	v_and_b32_e32 v57, 0xffff0000, v218
	v_lshlrev_b32_e32 v58, 16, v219
	v_and_b32_e32 v59, 0xffff0000, v219
.LBB0_1064:
	v_pk_fma_f32 v[38:39], v[38:39], v[54:55], v[66:67]
	v_pk_fma_f32 v[36:37], v[36:37], v[52:53], v[64:65]
	v_pk_fma_f32 v[34:35], v[34:35], v[50:51], v[58:59]
	s_and_b64 vcc, exec, s[14:15]
	v_pk_fma_f32 v[32:33], v[32:33], v[48:49], v[56:57]
	s_cbranch_vccnz .LBB0_1066
	global_store_dwordx4 v[76:77], v[36:39], off offset:512
	global_store_dwordx4 v[76:77], v[32:35], off offset:528

; __device__ __forceinline__ float bf_lo(unsigned v) { return __uint_as_float(v << 16); }
; __device__ __forceinline__ float bf_hi(unsigned v) { return __uint_as_float(v & 0xffff0000u); }
;     __device__ __forceinline__ void operator()(const f32x4 (&acc)[2][2][4][2], const Unit& u, int wr, int wc, int fr, int fq) const {
;     ...
;                 const int row = row0 + ai * HALF + m * 16; const size_t ro = (size_t)row * D + col0; float ss = 0.f;
; #pragma unroll
;                 for (int bj = 0; bj < 2; ++bj) {
;                     const size_t o = ro + bj * HALF;
;                     f32x4 s0, s1;
;                     if (srcf) { s0 = *(const f32x4*)(srcf + o); s1 = *(const f32x4*)(srcf + o + 4); }
;                     else { const u32x4 w = *(const u32x4*)(srcb + o); s0 = (f32x4){bf_lo(w.x), bf_hi(w.x), bf_lo(w.y), bf_hi(w.y)}; s1 = (f32x4){bf_lo(w.z), bf_hi(w.z), bf_lo(w.w), bf_hi(w.w)}; }
;                     const f32x4 v0 = acc[ai][bj][m][0] * cs[bj][0] + s0, v1 = acc[ai][bj][m][1] * cs[bj][1] + s1;
;                     ss += v0[0] * v0[0] + v0[1] * v0[1] + v0[2] * v0[2] + v0[3] * v0[3] + v1[0] * v1[0] + v1[1] * v1[1] + v1[2] * v1[2] + v1[3] * v1[3];
;                     if (dstf) { *(f32x4*)(dstf + o) = v0; *(f32x4*)(dstf + o + 4) = v1; }
.LBB0_1072:
	s_mov_b64 s[54:55], 0x50000
	v_lshl_add_u64 v[40:41], v[172:173], 0, s[54:55]
	s_and_b64 vcc, exec, s[12:13]
	v_lshl_add_u64 v[46:47], v[40:41], 2, s[28:29]
	s_cbranch_vccnz .LBB0_1119
	s_waitcnt lgkmcnt(0)
	global_load_dwordx4 v[32:35], v[46:47], off offset:16
	global_load_dwordx4 v[36:39], v[46:47], off
	v_lshl_add_u64 v[42:43], v[40:41], 1, s[84:85]
	s_waitcnt vmcnt(0)
	s_cbranch_execnz .LBB0_1075
.LBB0_1074:
	s_waitcnt lgkmcnt(0)
	s_waitcnt vmcnt(12)
	v_lshlrev_b32_e32 v36, 16, v220
	v_and_b32_e32 v37, 0xffff0000, v220
	v_lshlrev_b32_e32 v38, 16, v221
	v_and_b32_e32 v39, 0xffff0000, v221
	v_lshlrev_b32_e32 v32, 16, v222
	v_and_b32_e32 v33, 0xffff0000, v222
	v_lshlrev_b32_e32 v34, 16, v223
	v_and_b32_e32 v35, 0xffff0000, v223
.LBB0_1075:
	v_pk_fma_f32 v[30:31], v[30:31], v[70:71], v[38:39]
	v_pk_fma_f32 v[28:29], v[28:29], v[68:69], v[36:37]
	v_pk_fma_f32 v[26:27], v[26:27], v[62:63], v[34:35]
	s_waitcnt lgkmcnt(0)
	v_pk_fma_f32 v[24:25], v[24:25], v[60:61], v[32:33]
	s_and_b64 vcc, exec, s[14:15]
	v_lshl_add_u64 v[44:45], v[40:41], 2, s[20:21]
	s_cbranch_vccnz .LBB0_1077
	global_store_dwordx4 v[44:45], v[28:31], off
	global_store_dwordx4 v[44:45], v[24:27], off offset:16

; __device__ __forceinline__ float bf_lo(unsigned v) { return __uint_as_float(v << 16); }
; __device__ __forceinline__ float bf_hi(unsigned v) { return __uint_as_float(v & 0xffff0000u); }
;     __device__ __forceinline__ void operator()(const f32x4 (&acc)[2][2][4][2], const Unit& u, int wr, int wc, int fr, int fq) const {
;     ...
;                 const int row = row0 + ai * HALF + m * 16; const size_t ro = (size_t)row * D + col0; float ss = 0.f;
; #pragma unroll
;                 for (int bj = 0; bj < 2; ++bj) {
;                     const size_t o = ro + bj * HALF;
;                     f32x4 s0, s1;
;                     if (srcf) { s0 = *(const f32x4*)(srcf + o); s1 = *(const f32x4*)(srcf + o + 4); }
;                     else { const u32x4 w = *(const u32x4*)(srcb + o); s0 = (f32x4){bf_lo(w.x), bf_hi(w.x), bf_lo(w.y), bf_hi(w.y)}; s1 = (f32x4){bf_lo(w.z), bf_hi(w.z), bf_lo(w.w), bf_hi(w.w)}; }
;                     const f32x4 v0 = acc[ai][bj][m][0] * cs[bj][0] + s0, v1 = acc[ai][bj][m][1] * cs[bj][1] + s1;
;                     ss += v0[0] * v0[0] + v0[1] * v0[1] + v0[2] * v0[2] + v0[3] * v0[3] + v1[0] * v1[0] + v1[1] * v1[1] + v1[2] * v1[2] + v1[3] * v1[3];
;                     if (dstf) { *(f32x4*)(dstf + o) = v0; *(f32x4*)(dstf + o + 4) = v1; }
.LBB0_1079:
	s_and_b64 vcc, exec, s[12:13]
	s_cbranch_vccnz .LBB0_1120
	global_load_dwordx4 v[32:35], v[46:47], off offset:528
	global_load_dwordx4 v[36:39], v[46:47], off offset:512
	s_waitcnt vmcnt(0)
	s_cbranch_execnz .LBB0_1082
.LBB0_1081:
	s_waitcnt vmcnt(11)
	v_lshlrev_b32_e32 v36, 16, v224
	v_and_b32_e32 v37, 0xffff0000, v224
	v_lshlrev_b32_e32 v38, 16, v225
	v_and_b32_e32 v39, 0xffff0000, v225
	v_lshlrev_b32_e32 v32, 16, v226
	v_and_b32_e32 v33, 0xffff0000, v226
	v_lshlrev_b32_e32 v34, 16, v227
	v_and_b32_e32 v35, 0xffff0000, v227
.LBB0_1082:
	v_pk_fma_f32 v[22:23], v[22:23], v[54:55], v[38:39]
	v_pk_fma_f32 v[20:21], v[20:21], v[52:53], v[36:37]
	v_pk_fma_f32 v[18:19], v[18:19], v[50:51], v[34:35]
	s_and_b64 vcc, exec, s[14:15]
	v_pk_fma_f32 v[16:17], v[16:17], v[48:49], v[32:33]
	s_cbranch_vccnz .LBB0_1084
	global_store_dwordx4 v[44:45], v[20:23], off offset:512
	global_store_dwordx4 v[44:45], v[16:19], off offset:528

; __device__ __forceinline__ float bf_lo(unsigned v) { return __uint_as_float(v << 16); }
; __device__ __forceinline__ float bf_hi(unsigned v) { return __uint_as_float(v & 0xffff0000u); }
;     __device__ __forceinline__ void operator()(const f32x4 (&acc)[2][2][4][2], const Unit& u, int wr, int wc, int fr, int fq) const {
;     ...
;                 const int row = row0 + ai * HALF + m * 16; const size_t ro = (size_t)row * D + col0; float ss = 0.f;
; #pragma unroll
;                 for (int bj = 0; bj < 2; ++bj) {
;                     const size_t o = ro + bj * HALF;
;                     f32x4 s0, s1;
;                     if (srcf) { s0 = *(const f32x4*)(srcf + o); s1 = *(const f32x4*)(srcf + o + 4); }
;                     else { const u32x4 w = *(const u32x4*)(srcb + o); s0 = (f32x4){bf_lo(w.x), bf_hi(w.x), bf_lo(w.y), bf_hi(w.y)}; s1 = (f32x4){bf_lo(w.z), bf_hi(w.z), bf_lo(w.w), bf_hi(w.w)}; }
;                     const f32x4 v0 = acc[ai][bj][m][0] * cs[bj][0] + s0, v1 = acc[ai][bj][m][1] * cs[bj][1] + s1;
;                     ss += v0[0] * v0[0] + v0[1] * v0[1] + v0[2] * v0[2] + v0[3] * v0[3] + v1[0] * v1[0] + v1[1] * v1[1] + v1[2] * v1[2] + v1[3] * v1[3];
;                     if (dstf) { *(f32x4*)(dstf + o) = v0; *(f32x4*)(dstf + o + 4) = v1; }
.LBB0_1090:
	s_mov_b64 s[54:55], 0x58000
	v_lshl_add_u64 v[24:25], v[172:173], 0, s[54:55]
	s_and_b64 vcc, exec, s[12:13]
	v_lshl_add_u64 v[30:31], v[24:25], 2, s[28:29]
	s_cbranch_vccnz .LBB0_1121
	s_waitcnt lgkmcnt(0)
	global_load_dwordx4 v[16:19], v[30:31], off offset:16
	global_load_dwordx4 v[20:23], v[30:31], off
	v_lshl_add_u64 v[26:27], v[24:25], 1, s[84:85]
	s_waitcnt vmcnt(0)
	s_cbranch_execnz .LBB0_1093
.LBB0_1092:
	s_waitcnt lgkmcnt(0)
	s_waitcnt vmcnt(10)
	v_lshlrev_b32_e32 v20, 16, v228
	v_and_b32_e32 v21, 0xffff0000, v228
	v_lshlrev_b32_e32 v22, 16, v229
	v_and_b32_e32 v23, 0xffff0000, v229
	v_lshlrev_b32_e32 v16, 16, v230
	v_and_b32_e32 v17, 0xffff0000, v230
	v_lshlrev_b32_e32 v18, 16, v231
	v_and_b32_e32 v19, 0xffff0000, v231
.LBB0_1093:
	v_pk_fma_f32 v[14:15], v[14:15], v[70:71], v[22:23]
	v_pk_fma_f32 v[12:13], v[12:13], v[68:69], v[20:21]
	v_pk_fma_f32 v[10:11], v[10:11], v[62:63], v[18:19]
	s_waitcnt lgkmcnt(0)
	v_pk_fma_f32 v[8:9], v[8:9], v[60:61], v[16:17]
	s_and_b64 vcc, exec, s[14:15]
	v_lshl_add_u64 v[28:29], v[24:25], 2, s[20:21]
	s_cbranch_vccnz .LBB0_1095
	global_store_dwordx4 v[28:29], v[12:15], off
	global_store_dwordx4 v[28:29], v[8:11], off offset:16

; __device__ __forceinline__ float bf_lo(unsigned v) { return __uint_as_float(v << 16); }
; __device__ __forceinline__ float bf_hi(unsigned v) { return __uint_as_float(v & 0xffff0000u); }
;     __device__ __forceinline__ void operator()(const f32x4 (&acc)[2][2][4][2], const Unit& u, int wr, int wc, int fr, int fq) const {
;     ...
;                 const int row = row0 + ai * HALF + m * 16; const size_t ro = (size_t)row * D + col0; float ss = 0.f;
; #pragma unroll
;                 for (int bj = 0; bj < 2; ++bj) {
;                     const size_t o = ro + bj * HALF;
;                     f32x4 s0, s1;
;                     if (srcf) { s0 = *(const f32x4*)(srcf + o); s1 = *(const f32x4*)(srcf + o + 4); }
;                     else { const u32x4 w = *(const u32x4*)(srcb + o); s0 = (f32x4){bf_lo(w.x), bf_hi(w.x), bf_lo(w.y), bf_hi(w.y)}; s1 = (f32x4){bf_lo(w.z), bf_hi(w.z), bf_lo(w.w), bf_hi(w.w)}; }
;                     const f32x4 v0 = acc[ai][bj][m][0] * cs[bj][0] + s0, v1 = acc[ai][bj][m][1] * cs[bj][1] + s1;
;                     ss += v0[0] * v0[0] + v0[1] * v0[1] + v0[2] * v0[2] + v0[3] * v0[3] + v1[0] * v1[0] + v1[1] * v1[1] + v1[2] * v1[2] + v1[3] * v1[3];
;                     if (dstf) { *(f32x4*)(dstf + o) = v0; *(f32x4*)(dstf + o + 4) = v1; }
.LBB0_1097:
	s_and_b64 vcc, exec, s[12:13]
	s_cbranch_vccnz .LBB0_1122
	global_load_dwordx4 v[16:19], v[30:31], off offset:528
	global_load_dwordx4 v[20:23], v[30:31], off offset:512
	s_waitcnt vmcnt(0)
	s_cbranch_execnz .LBB0_1100
.LBB0_1099:
	s_waitcnt vmcnt(9)
	v_lshlrev_b32_e32 v20, 16, v232
	v_and_b32_e32 v21, 0xffff0000, v232
	v_lshlrev_b32_e32 v22, 16, v233
	v_and_b32_e32 v23, 0xffff0000, v233
	v_lshlrev_b32_e32 v16, 16, v234
	v_and_b32_e32 v17, 0xffff0000, v234
	v_lshlrev_b32_e32 v18, 16, v235
	v_and_b32_e32 v19, 0xffff0000, v235
.LBB0_1100:
	v_pk_fma_f32 v[6:7], v[6:7], v[54:55], v[22:23]
	v_pk_fma_f32 v[4:5], v[4:5], v[52:53], v[20:21]
	v_pk_fma_f32 v[2:3], v[2:3], v[50:51], v[18:19]
	s_and_b64 vcc, exec, s[14:15]
	v_pk_fma_f32 v[0:1], v[0:1], v[48:49], v[16:17]
	s_cbranch_vccnz .LBB0_1102
	global_store_dwordx4 v[28:29], v[4:7], off offset:512
	global_store_dwordx4 v[28:29], v[0:3], off offset:528

; __device__ __forceinline__ float bf_lo(unsigned v) { return __uint_as_float(v << 16); }
; __device__ __forceinline__ float bf_hi(unsigned v) { return __uint_as_float(v & 0xffff0000u); }
;     __device__ __forceinline__ void operator()(const f32x4 (&acc)[2][2][4][2], const Unit& u, int wr, int wc, int fr, int fq) const {
;     ...
;                     if (srcf) { s0 = *(const f32x4*)(srcf + o); s1 = *(const f32x4*)(srcf + o + 4); }
;                     else { const u32x4 w = *(const u32x4*)(srcb + o); s0 = (f32x4){bf_lo(w.x), bf_hi(w.x), bf_lo(w.y), bf_hi(w.y)}; s1 = (f32x4){bf_lo(w.z), bf_hi(w.z), bf_lo(w.w), bf_hi(w.w)}; }
.LBB0_1107:
	v_lshlrev_b32_e32 v178, 1, v172
	global_load_dwordx4 v[208:211], v178, s[84:85]
	global_load_dwordx4 v[212:215], v178, s[84:85] offset:256
	v_add_u32_e32 v179, 0x10000, v178
	global_load_dwordx4 v[216:219], v179, s[84:85]
	global_load_dwordx4 v[220:223], v179, s[84:85] offset:256
	v_add_u32_e32 v179, 0x20000, v178
	global_load_dwordx4 v[224:227], v179, s[84:85]
	global_load_dwordx4 v[228:231], v179, s[84:85] offset:256
	v_add_u32_e32 v179, 0x30000, v178
	global_load_dwordx4 v[232:235], v179, s[84:85]
	global_load_dwordx4 v[246:249], v179, s[84:85] offset:256
	v_add_u32_e32 v179, 0x80000, v178
	global_load_dwordx4 v[250:253], v179, s[84:85]
	s_branch .LBB0_966
